# v7 plus first LDS fragment reads hoisted above the DMA issue block in all ten GEMM K loops
# speedup vs baseline: 1.0395x; 1.0056x over previous
.LBB0_130:
	v_add_u32_e32 v164, v168, v189
	v_add_u32_e32 v169, v146, v189
	s_waitcnt lgkmcnt(3)
	v_mfma_f32_32x32x16_bf16 v[0:15], v[128:131], v[132:135], v[0:15]
	ds_read_b128 v[156:159], v164
	s_add_u32 s0, s0, 0x80
	s_addc_u32 s1, s1, 0
	s_add_i32 s47, s47, 1
	s_cmpk_lg_i32 s0, 0x800
	s_mov_b32 s48, s52
	v_mfma_f32_32x32x16_bf16 v[16:31], v[152:155], v[132:135], v[16:31]
	ds_read_b128 v[132:135], v164 offset:4096
	s_waitcnt lgkmcnt(4)
	v_mfma_f32_32x32x16_bf16 v[32:47], v[128:131], v[136:139], v[32:47]
	ds_read_b128 v[160:163], v164 offset:8192
	v_mfma_f32_32x32x16_bf16 v[48:63], v[152:155], v[136:139], v[48:63]
	ds_read_b128 v[136:139], v164 offset:12288
	s_waitcnt lgkmcnt(5)
	v_mfma_f32_32x32x16_bf16 v[64:79], v[128:131], v[140:143], v[64:79]
	ds_read_b128 v[164:167], v169 offset:32768
	v_mfma_f32_32x32x16_bf16 v[80:95], v[152:155], v[140:143], v[80:95]
	ds_read_b128 v[140:143], v169 offset:36864
	v_add_u32_e32 v169, v168, v190
	s_waitcnt lgkmcnt(6)
	v_mfma_f32_32x32x16_bf16 v[96:111], v[128:131], v[148:151], v[96:111]
	v_mfma_f32_32x32x16_bf16 v[112:127], v[152:155], v[148:151], v[112:127]
	s_waitcnt lgkmcnt(1)
	v_mfma_f32_32x32x16_bf16 v[0:15], v[164:167], v[156:159], v[0:15]
	ds_read_b128 v[128:131], v169
	s_waitcnt lgkmcnt(1)
	v_mfma_f32_32x32x16_bf16 v[16:31], v[140:143], v[156:159], v[16:31]
	ds_read_b128 v[148:151], v169 offset:4096
	v_mfma_f32_32x32x16_bf16 v[32:47], v[164:167], v[132:135], v[32:47]
	ds_read_b128 v[152:155], v169 offset:8192
	v_mfma_f32_32x32x16_bf16 v[48:63], v[140:143], v[132:135], v[48:63]
	ds_read_b128 v[132:135], v169 offset:12288
	v_add_u32_e32 v169, v146, v190
	v_add_u32_e32 v146, v146, v191
	v_mfma_f32_32x32x16_bf16 v[64:79], v[164:167], v[160:163], v[64:79]
	ds_read_b128 v[156:159], v169 offset:32768
	v_mfma_f32_32x32x16_bf16 v[80:95], v[140:143], v[160:163], v[80:95]
	ds_read_b128 v[160:163], v169 offset:36864
	v_mfma_f32_32x32x16_bf16 v[96:111], v[164:167], v[136:139], v[96:111]
	v_add_u32_e32 v164, v168, v191
	v_mfma_f32_32x32x16_bf16 v[112:127], v[140:143], v[136:139], v[112:127]
	s_waitcnt lgkmcnt(1)
	v_mfma_f32_32x32x16_bf16 v[0:15], v[156:159], v[128:131], v[0:15]
	ds_read_b128 v[136:139], v164
	s_waitcnt lgkmcnt(1)
	v_mfma_f32_32x32x16_bf16 v[16:31], v[160:163], v[128:131], v[16:31]
	ds_read_b128 v[128:131], v164 offset:4096
	v_mfma_f32_32x32x16_bf16 v[32:47], v[156:159], v[148:151], v[32:47]
	ds_read_b128 v[140:143], v164 offset:8192
	v_mfma_f32_32x32x16_bf16 v[48:63], v[160:163], v[148:151], v[48:63]
	ds_read_b128 v[148:151], v164 offset:12288
	v_mfma_f32_32x32x16_bf16 v[64:79], v[156:159], v[152:155], v[64:79]
	ds_read_b128 v[164:167], v146 offset:32768
	v_mfma_f32_32x32x16_bf16 v[80:95], v[160:163], v[152:155], v[80:95]
	ds_read_b128 v[152:155], v146 offset:36864
	v_mfma_f32_32x32x16_bf16 v[96:111], v[156:159], v[132:135], v[96:111]
	v_mfma_f32_32x32x16_bf16 v[112:127], v[160:163], v[132:135], v[112:127]
	s_waitcnt lgkmcnt(1)
	v_mfma_f32_32x32x16_bf16 v[0:15], v[164:167], v[136:139], v[0:15]
	s_waitcnt lgkmcnt(0)
	v_mfma_f32_32x32x16_bf16 v[16:31], v[152:155], v[136:139], v[16:31]
	v_mfma_f32_32x32x16_bf16 v[32:47], v[164:167], v[128:131], v[32:47]
	v_mfma_f32_32x32x16_bf16 v[48:63], v[152:155], v[128:131], v[48:63]
	v_mfma_f32_32x32x16_bf16 v[64:79], v[164:167], v[140:143], v[64:79]
	v_mfma_f32_32x32x16_bf16 v[80:95], v[152:155], v[140:143], v[80:95]
	v_mfma_f32_32x32x16_bf16 v[96:111], v[164:167], v[148:151], v[96:111]
	v_mfma_f32_32x32x16_bf16 v[112:127], v[152:155], v[148:151], v[112:127]
	s_cbranch_scc0 .LBB0_135

.Lkin_L0:
	s_and_b32 s4, s48, 0x10000
	v_or_b32_e32 v146, s4, v187
	v_add_u32_e32 v152, v146, v188
	ds_read_b128 v[128:131], v152 offset:32768
	ds_read_b128 v[152:155], v152 offset:36864
	v_add_u32_e32 v168, s4, v186
	v_add_u32_e32 v148, v168, v188
	ds_read_b128 v[132:135], v148
	ds_read_b128 v[136:139], v148 offset:4096
	ds_read_b128 v[140:143], v148 offset:8192
	ds_read_b128 v[148:151], v148 offset:12288
	s_cmp_lt_u32 s47, 15
	s_mov_b64 s[4:5], -1
	s_cbranch_scc1 .LBB0_133
	s_add_i32 s52, s48, 0x10000
	s_mov_b64 s[4:5], 0

.LBB0_312:
	s_waitcnt lgkmcnt(3)
	v_mfma_f32_32x32x16_bf16 v[48:63], v[130:133], v[134:137], v[48:63]
	ds_read_b128 v[166:169], v157
	s_add_u32 s18, s18, 0x80
	s_addc_u32 s19, s19, 0
	s_add_i32 s58, s58, 1
	s_cmpk_lg_i32 s18, 0x400
	s_mov_b32 s59, s60
	v_mfma_f32_32x32x16_bf16 v[32:47], v[162:165], v[134:137], v[32:47]
	ds_read_b128 v[134:137], v157 offset:4096
	s_waitcnt lgkmcnt(4)
	v_mfma_f32_32x32x16_bf16 v[16:31], v[130:133], v[138:141], v[16:31]
	ds_read_b128 v[170:173], v157 offset:8192
	v_mfma_f32_32x32x16_bf16 v[0:15], v[162:165], v[138:141], v[0:15]
	ds_read_b128 v[138:141], v157 offset:12288
	v_add_u32_e32 v157, v128, v154
	s_waitcnt lgkmcnt(5)
	v_mfma_f32_32x32x16_bf16 v[64:79], v[130:133], v[142:145], v[64:79]
	ds_read_b128 v[174:177], v157 offset:32768
	v_mfma_f32_32x32x16_bf16 v[80:95], v[162:165], v[142:145], v[80:95]
	ds_read_b128 v[142:145], v157 offset:36864
	v_add_u32_e32 v157, v180, v155
	s_waitcnt lgkmcnt(6)
	v_mfma_f32_32x32x16_bf16 v[96:111], v[130:133], v[158:161], v[96:111]
	v_mfma_f32_32x32x16_bf16 v[112:127], v[162:165], v[158:161], v[112:127]
	s_waitcnt lgkmcnt(1)
	v_mfma_f32_32x32x16_bf16 v[48:63], v[174:177], v[166:169], v[48:63]
	ds_read_b128 v[130:133], v157
	s_waitcnt lgkmcnt(1)
	v_mfma_f32_32x32x16_bf16 v[32:47], v[142:145], v[166:169], v[32:47]
	ds_read_b128 v[158:161], v157 offset:4096
	v_mfma_f32_32x32x16_bf16 v[16:31], v[174:177], v[134:137], v[16:31]
	ds_read_b128 v[162:165], v157 offset:8192
	v_mfma_f32_32x32x16_bf16 v[0:15], v[142:145], v[134:137], v[0:15]
	ds_read_b128 v[134:137], v157 offset:12288
	v_add_u32_e32 v157, v128, v155
	v_add_u32_e32 v128, v128, v156
	v_mfma_f32_32x32x16_bf16 v[64:79], v[174:177], v[170:173], v[64:79]
	ds_read_b128 v[166:169], v157 offset:32768
	v_mfma_f32_32x32x16_bf16 v[80:95], v[142:145], v[170:173], v[80:95]
	ds_read_b128 v[170:173], v157 offset:36864
	v_add_u32_e32 v157, v180, v156
	v_mfma_f32_32x32x16_bf16 v[96:111], v[174:177], v[138:141], v[96:111]
	v_mfma_f32_32x32x16_bf16 v[112:127], v[142:145], v[138:141], v[112:127]
	s_waitcnt lgkmcnt(1)
	v_mfma_f32_32x32x16_bf16 v[48:63], v[166:169], v[130:133], v[48:63]
	ds_read_b128 v[138:141], v157
	s_waitcnt lgkmcnt(1)
	v_mfma_f32_32x32x16_bf16 v[32:47], v[170:173], v[130:133], v[32:47]
	ds_read_b128 v[130:133], v157 offset:4096
	v_mfma_f32_32x32x16_bf16 v[16:31], v[166:169], v[158:161], v[16:31]
	ds_read_b128 v[142:145], v157 offset:8192
	v_mfma_f32_32x32x16_bf16 v[0:15], v[170:173], v[158:161], v[0:15]
	ds_read_b128 v[158:161], v157 offset:12288
	v_mfma_f32_32x32x16_bf16 v[64:79], v[166:169], v[162:165], v[64:79]
	ds_read_b128 v[174:177], v128 offset:32768
	v_mfma_f32_32x32x16_bf16 v[80:95], v[170:173], v[162:165], v[80:95]
	ds_read_b128 v[162:165], v128 offset:36864
	v_mfma_f32_32x32x16_bf16 v[96:111], v[166:169], v[134:137], v[96:111]
	v_mfma_f32_32x32x16_bf16 v[112:127], v[170:173], v[134:137], v[112:127]
	s_waitcnt lgkmcnt(1)
	v_mfma_f32_32x32x16_bf16 v[48:63], v[174:177], v[138:141], v[48:63]
	s_waitcnt lgkmcnt(0)
	v_mfma_f32_32x32x16_bf16 v[32:47], v[162:165], v[138:141], v[32:47]
	v_mfma_f32_32x32x16_bf16 v[16:31], v[174:177], v[130:133], v[16:31]
	v_mfma_f32_32x32x16_bf16 v[0:15], v[162:165], v[130:133], v[0:15]
	v_mfma_f32_32x32x16_bf16 v[64:79], v[174:177], v[142:145], v[64:79]
	v_mfma_f32_32x32x16_bf16 v[80:95], v[162:165], v[142:145], v[80:95]
	v_mfma_f32_32x32x16_bf16 v[96:111], v[174:177], v[158:161], v[96:111]
	v_mfma_f32_32x32x16_bf16 v[112:127], v[162:165], v[158:161], v[112:127]
	s_cbranch_scc0 .LBB0_317
.LBB0_313:
	s_waitcnt vmcnt(0)
	s_barrier
	s_and_b32 s22, s59, 0x10000
	v_or_b32_e32 v128, s22, v152
	v_add_u32_e32 v157, v128, v153
	ds_read_b128 v[130:133], v157 offset:32768
	ds_read_b128 v[162:165], v157 offset:36864
	v_add_u32_e32 v180, s22, v151
	v_add_u32_e32 v158, v180, v153
	ds_read_b128 v[134:137], v158
	ds_read_b128 v[138:141], v158 offset:4096
	ds_read_b128 v[142:145], v158 offset:8192
	v_add_u32_e32 v157, v180, v154
	ds_read_b128 v[158:161], v158 offset:12288
	s_cmp_lt_u32 s58, 7
	s_mov_b64 s[22:23], -1
	s_cbranch_scc1 .LBB0_315
	s_add_i32 s60, s59, 0x10000
	s_mov_b64 s[22:23], 0

.LBB0_326:
	s_waitcnt lgkmcnt(3)
	v_mfma_f32_32x32x16_bf16 v[48:63], v[130:133], v[134:137], v[48:63]
	ds_read_b128 v[166:169], v157
	s_add_u32 s20, s20, 0x80
	s_addc_u32 s21, s21, 0
	s_add_i32 s58, s58, 1
	s_cmpk_lg_i32 s20, 0x400
	s_mov_b32 s59, s60
	v_mfma_f32_32x32x16_bf16 v[32:47], v[162:165], v[134:137], v[32:47]
	ds_read_b128 v[134:137], v157 offset:4096
	s_waitcnt lgkmcnt(4)
	v_mfma_f32_32x32x16_bf16 v[16:31], v[130:133], v[138:141], v[16:31]
	ds_read_b128 v[170:173], v157 offset:8192
	v_mfma_f32_32x32x16_bf16 v[0:15], v[162:165], v[138:141], v[0:15]
	ds_read_b128 v[138:141], v157 offset:12288
	v_add_u32_e32 v157, v128, v154
	s_waitcnt lgkmcnt(5)
	v_mfma_f32_32x32x16_bf16 v[64:79], v[130:133], v[142:145], v[64:79]
	ds_read_b128 v[174:177], v157 offset:32768
	v_mfma_f32_32x32x16_bf16 v[80:95], v[162:165], v[142:145], v[80:95]
	ds_read_b128 v[142:145], v157 offset:36864
	v_add_u32_e32 v157, v180, v155
	s_waitcnt lgkmcnt(6)
	v_mfma_f32_32x32x16_bf16 v[96:111], v[130:133], v[158:161], v[96:111]
	v_mfma_f32_32x32x16_bf16 v[112:127], v[162:165], v[158:161], v[112:127]
	s_waitcnt lgkmcnt(1)
	v_mfma_f32_32x32x16_bf16 v[48:63], v[174:177], v[166:169], v[48:63]
	ds_read_b128 v[130:133], v157
	s_waitcnt lgkmcnt(1)
	v_mfma_f32_32x32x16_bf16 v[32:47], v[142:145], v[166:169], v[32:47]
	ds_read_b128 v[158:161], v157 offset:4096
	v_mfma_f32_32x32x16_bf16 v[16:31], v[174:177], v[134:137], v[16:31]
	ds_read_b128 v[162:165], v157 offset:8192
	v_mfma_f32_32x32x16_bf16 v[0:15], v[142:145], v[134:137], v[0:15]
	ds_read_b128 v[134:137], v157 offset:12288
	v_add_u32_e32 v157, v128, v155
	v_add_u32_e32 v128, v128, v156
	v_mfma_f32_32x32x16_bf16 v[64:79], v[174:177], v[170:173], v[64:79]
	ds_read_b128 v[166:169], v157 offset:32768
	v_mfma_f32_32x32x16_bf16 v[80:95], v[142:145], v[170:173], v[80:95]
	ds_read_b128 v[170:173], v157 offset:36864
	v_add_u32_e32 v157, v180, v156
	v_mfma_f32_32x32x16_bf16 v[96:111], v[174:177], v[138:141], v[96:111]
	v_mfma_f32_32x32x16_bf16 v[112:127], v[142:145], v[138:141], v[112:127]
	s_waitcnt lgkmcnt(1)
	v_mfma_f32_32x32x16_bf16 v[48:63], v[166:169], v[130:133], v[48:63]
	ds_read_b128 v[138:141], v157
	s_waitcnt lgkmcnt(1)
	v_mfma_f32_32x32x16_bf16 v[32:47], v[170:173], v[130:133], v[32:47]
	ds_read_b128 v[130:133], v157 offset:4096
	v_mfma_f32_32x32x16_bf16 v[16:31], v[166:169], v[158:161], v[16:31]
	ds_read_b128 v[142:145], v157 offset:8192
	v_mfma_f32_32x32x16_bf16 v[0:15], v[170:173], v[158:161], v[0:15]
	ds_read_b128 v[158:161], v157 offset:12288
	v_mfma_f32_32x32x16_bf16 v[64:79], v[166:169], v[162:165], v[64:79]
	ds_read_b128 v[174:177], v128 offset:32768
	v_mfma_f32_32x32x16_bf16 v[80:95], v[170:173], v[162:165], v[80:95]
	ds_read_b128 v[162:165], v128 offset:36864
	v_mfma_f32_32x32x16_bf16 v[96:111], v[166:169], v[134:137], v[96:111]
	v_mfma_f32_32x32x16_bf16 v[112:127], v[170:173], v[134:137], v[112:127]
	s_waitcnt lgkmcnt(1)
	v_mfma_f32_32x32x16_bf16 v[48:63], v[174:177], v[138:141], v[48:63]
	s_waitcnt lgkmcnt(0)
	v_mfma_f32_32x32x16_bf16 v[32:47], v[162:165], v[138:141], v[32:47]
	v_mfma_f32_32x32x16_bf16 v[16:31], v[174:177], v[130:133], v[16:31]
	v_mfma_f32_32x32x16_bf16 v[0:15], v[162:165], v[130:133], v[0:15]
	v_mfma_f32_32x32x16_bf16 v[64:79], v[174:177], v[142:145], v[64:79]
	v_mfma_f32_32x32x16_bf16 v[80:95], v[162:165], v[142:145], v[80:95]
	v_mfma_f32_32x32x16_bf16 v[96:111], v[174:177], v[158:161], v[96:111]
	v_mfma_f32_32x32x16_bf16 v[112:127], v[162:165], v[158:161], v[112:127]
	s_cbranch_scc0 .LBB0_331

.LBB0_396:
	s_waitcnt lgkmcnt(3)
	v_mfma_f32_32x32x16_bf16 v[48:63], v[130:133], v[134:137], v[48:63]
	ds_read_b128 v[164:167], v155
	s_add_u32 s4, s4, 0x80
	s_addc_u32 s5, s5, 0
	s_add_i32 s43, s43, 1
	s_cmpk_lg_i32 s4, 0x800
	s_mov_b32 s44, s45
	v_mfma_f32_32x32x16_bf16 v[32:47], v[160:163], v[134:137], v[32:47]
	ds_read_b128 v[134:137], v155 offset:4096
	s_waitcnt lgkmcnt(4)
	v_mfma_f32_32x32x16_bf16 v[16:31], v[130:133], v[138:141], v[16:31]
	ds_read_b128 v[168:171], v155 offset:8192
	v_mfma_f32_32x32x16_bf16 v[0:15], v[160:163], v[138:141], v[0:15]
	ds_read_b128 v[138:141], v155 offset:12288
	v_add_u32_e32 v155, v128, v152
	s_waitcnt lgkmcnt(5)
	v_mfma_f32_32x32x16_bf16 v[64:79], v[130:133], v[142:145], v[64:79]
	ds_read_b128 v[172:175], v155 offset:32768
	v_mfma_f32_32x32x16_bf16 v[80:95], v[160:163], v[142:145], v[80:95]
	ds_read_b128 v[142:145], v155 offset:36864
	v_add_u32_e32 v155, v176, v153
	s_waitcnt lgkmcnt(6)
	v_mfma_f32_32x32x16_bf16 v[96:111], v[130:133], v[156:159], v[96:111]
	v_mfma_f32_32x32x16_bf16 v[112:127], v[160:163], v[156:159], v[112:127]
	s_waitcnt lgkmcnt(1)
	v_mfma_f32_32x32x16_bf16 v[48:63], v[172:175], v[164:167], v[48:63]
	ds_read_b128 v[130:133], v155
	s_waitcnt lgkmcnt(1)
	v_mfma_f32_32x32x16_bf16 v[32:47], v[142:145], v[164:167], v[32:47]
	ds_read_b128 v[156:159], v155 offset:4096
	v_mfma_f32_32x32x16_bf16 v[16:31], v[172:175], v[134:137], v[16:31]
	ds_read_b128 v[160:163], v155 offset:8192
	v_mfma_f32_32x32x16_bf16 v[0:15], v[142:145], v[134:137], v[0:15]
	ds_read_b128 v[134:137], v155 offset:12288
	v_add_u32_e32 v155, v128, v153
	v_add_u32_e32 v128, v128, v154
	v_mfma_f32_32x32x16_bf16 v[64:79], v[172:175], v[168:171], v[64:79]
	ds_read_b128 v[164:167], v155 offset:32768
	v_mfma_f32_32x32x16_bf16 v[80:95], v[142:145], v[168:171], v[80:95]
	ds_read_b128 v[168:171], v155 offset:36864
	v_add_u32_e32 v155, v176, v154
	v_mfma_f32_32x32x16_bf16 v[96:111], v[172:175], v[138:141], v[96:111]
	v_mfma_f32_32x32x16_bf16 v[112:127], v[142:145], v[138:141], v[112:127]
	s_waitcnt lgkmcnt(1)
	v_mfma_f32_32x32x16_bf16 v[48:63], v[164:167], v[130:133], v[48:63]
	ds_read_b128 v[138:141], v155
	s_waitcnt lgkmcnt(1)
	v_mfma_f32_32x32x16_bf16 v[32:47], v[168:171], v[130:133], v[32:47]
	ds_read_b128 v[130:133], v155 offset:4096
	v_mfma_f32_32x32x16_bf16 v[16:31], v[164:167], v[156:159], v[16:31]
	ds_read_b128 v[142:145], v155 offset:8192
	v_mfma_f32_32x32x16_bf16 v[0:15], v[168:171], v[156:159], v[0:15]
	ds_read_b128 v[156:159], v155 offset:12288
	v_mfma_f32_32x32x16_bf16 v[64:79], v[164:167], v[160:163], v[64:79]
	ds_read_b128 v[172:175], v128 offset:32768
	v_mfma_f32_32x32x16_bf16 v[80:95], v[168:171], v[160:163], v[80:95]
	ds_read_b128 v[160:163], v128 offset:36864
	v_mfma_f32_32x32x16_bf16 v[96:111], v[164:167], v[134:137], v[96:111]
	v_mfma_f32_32x32x16_bf16 v[112:127], v[168:171], v[134:137], v[112:127]
	s_waitcnt lgkmcnt(1)
	v_mfma_f32_32x32x16_bf16 v[48:63], v[172:175], v[138:141], v[48:63]
	s_waitcnt lgkmcnt(0)
	v_mfma_f32_32x32x16_bf16 v[32:47], v[160:163], v[138:141], v[32:47]
	v_mfma_f32_32x32x16_bf16 v[16:31], v[172:175], v[130:133], v[16:31]
	v_mfma_f32_32x32x16_bf16 v[0:15], v[160:163], v[130:133], v[0:15]
	v_mfma_f32_32x32x16_bf16 v[64:79], v[172:175], v[142:145], v[64:79]
	v_mfma_f32_32x32x16_bf16 v[80:95], v[160:163], v[142:145], v[80:95]
	v_mfma_f32_32x32x16_bf16 v[96:111], v[172:175], v[156:159], v[96:111]
	v_mfma_f32_32x32x16_bf16 v[112:127], v[160:163], v[156:159], v[112:127]
	s_cbranch_scc0 .LBB0_401
.LBB0_397:
	s_waitcnt vmcnt(0)
	s_barrier
	s_and_b32 s10, s44, 0x10000
	v_or_b32_e32 v128, s10, v150
	v_add_u32_e32 v155, v128, v151
	ds_read_b128 v[130:133], v155 offset:32768
	ds_read_b128 v[160:163], v155 offset:36864
	v_add_u32_e32 v176, s10, v149
	v_add_u32_e32 v156, v176, v151
	ds_read_b128 v[134:137], v156
	ds_read_b128 v[138:141], v156 offset:4096
	ds_read_b128 v[142:145], v156 offset:8192
	v_add_u32_e32 v155, v176, v152
	ds_read_b128 v[156:159], v156 offset:12288
	s_cmp_lt_u32 s43, 15
	s_mov_b64 s[10:11], -1
	s_cbranch_scc1 .LBB0_399
	s_add_i32 s45, s44, 0x10000
	s_mov_b64 s[10:11], 0

.LBB0_469:
	s_waitcnt lgkmcnt(3)
	v_mfma_f32_32x32x16_bf16 v[112:127], v[128:131], v[132:135], v[112:127]
	ds_read_b128 v[168:171], v150
	s_add_u32 s0, s0, 0x80
	s_addc_u32 s1, s1, 0
	s_add_i32 s48, s48, 1
	s_cmpk_lg_i32 s0, 0x800
	s_mov_b32 s49, s50
	v_mfma_f32_32x32x16_bf16 v[96:111], v[164:167], v[132:135], v[96:111]
	ds_read_b128 v[132:135], v150 offset:4096
	s_waitcnt lgkmcnt(4)
	v_mfma_f32_32x32x16_bf16 v[80:95], v[128:131], v[136:139], v[80:95]
	ds_read_b128 v[172:175], v150 offset:8192
	v_mfma_f32_32x32x16_bf16 v[64:79], v[164:167], v[136:139], v[64:79]
	ds_read_b128 v[136:139], v150 offset:12288
	v_add_u32_e32 v150, v144, v158
	s_waitcnt lgkmcnt(5)
	v_mfma_f32_32x32x16_bf16 v[48:63], v[128:131], v[140:143], v[48:63]
	ds_read_b128 v[186:189], v150 offset:32768
	v_mfma_f32_32x32x16_bf16 v[32:47], v[164:167], v[140:143], v[32:47]
	ds_read_b128 v[140:143], v150 offset:36864
	v_add_u32_e32 v150, v151, v159
	s_waitcnt lgkmcnt(6)
	v_mfma_f32_32x32x16_bf16 v[16:31], v[128:131], v[146:149], v[16:31]
	v_mfma_f32_32x32x16_bf16 v[0:15], v[164:167], v[146:149], v[0:15]
	s_waitcnt lgkmcnt(1)
	v_mfma_f32_32x32x16_bf16 v[112:127], v[186:189], v[168:171], v[112:127]
	ds_read_b128 v[128:131], v150
	s_waitcnt lgkmcnt(1)
	v_mfma_f32_32x32x16_bf16 v[96:111], v[140:143], v[168:171], v[96:111]
	ds_read_b128 v[146:149], v150 offset:4096
	v_mfma_f32_32x32x16_bf16 v[80:95], v[186:189], v[132:135], v[80:95]
	ds_read_b128 v[164:167], v150 offset:8192
	v_mfma_f32_32x32x16_bf16 v[64:79], v[140:143], v[132:135], v[64:79]
	ds_read_b128 v[132:135], v150 offset:12288
	v_add_u32_e32 v150, v144, v159
	v_add_u32_e32 v144, v144, v160
	v_mfma_f32_32x32x16_bf16 v[48:63], v[186:189], v[172:175], v[48:63]
	ds_read_b128 v[168:171], v150 offset:32768
	v_mfma_f32_32x32x16_bf16 v[32:47], v[140:143], v[172:175], v[32:47]
	ds_read_b128 v[172:175], v150 offset:36864
	v_add_u32_e32 v150, v151, v160
	v_mfma_f32_32x32x16_bf16 v[16:31], v[186:189], v[136:139], v[16:31]
	v_mfma_f32_32x32x16_bf16 v[0:15], v[140:143], v[136:139], v[0:15]
	s_waitcnt lgkmcnt(1)
	v_mfma_f32_32x32x16_bf16 v[112:127], v[168:171], v[128:131], v[112:127]
	ds_read_b128 v[136:139], v150
	s_waitcnt lgkmcnt(1)
	v_mfma_f32_32x32x16_bf16 v[96:111], v[172:175], v[128:131], v[96:111]
	ds_read_b128 v[128:131], v150 offset:4096
	v_mfma_f32_32x32x16_bf16 v[80:95], v[168:171], v[146:149], v[80:95]
	ds_read_b128 v[140:143], v150 offset:8192
	v_mfma_f32_32x32x16_bf16 v[64:79], v[172:175], v[146:149], v[64:79]
	ds_read_b128 v[146:149], v150 offset:12288
	v_mfma_f32_32x32x16_bf16 v[48:63], v[168:171], v[164:167], v[48:63]
	ds_read_b128 v[186:189], v144 offset:32768
	v_mfma_f32_32x32x16_bf16 v[32:47], v[172:175], v[164:167], v[32:47]
	ds_read_b128 v[164:167], v144 offset:36864
	v_mfma_f32_32x32x16_bf16 v[16:31], v[168:171], v[132:135], v[16:31]
	v_mfma_f32_32x32x16_bf16 v[0:15], v[172:175], v[132:135], v[0:15]
	s_waitcnt lgkmcnt(1)
	v_mfma_f32_32x32x16_bf16 v[112:127], v[186:189], v[136:139], v[112:127]
	s_waitcnt lgkmcnt(0)
	v_mfma_f32_32x32x16_bf16 v[96:111], v[164:167], v[136:139], v[96:111]
	v_mfma_f32_32x32x16_bf16 v[80:95], v[186:189], v[128:131], v[80:95]
	v_mfma_f32_32x32x16_bf16 v[64:79], v[164:167], v[128:131], v[64:79]
	v_mfma_f32_32x32x16_bf16 v[48:63], v[186:189], v[140:143], v[48:63]
	v_mfma_f32_32x32x16_bf16 v[32:47], v[164:167], v[140:143], v[32:47]
	v_mfma_f32_32x32x16_bf16 v[16:31], v[186:189], v[146:149], v[16:31]
	v_mfma_f32_32x32x16_bf16 v[0:15], v[164:167], v[146:149], v[0:15]
	s_cbranch_scc0 .LBB0_474
.LBB0_470:
	s_waitcnt vmcnt(0)
	s_barrier
	s_and_b32 s18, s49, 0x10000
	v_or_b32_e32 v144, s18, v156
	v_add_u32_e32 v150, v144, v157
	ds_read_b128 v[128:131], v150 offset:32768
	ds_read_b128 v[164:167], v150 offset:36864
	v_add_u32_e32 v151, s18, v155
	v_add_u32_e32 v146, v151, v157
	ds_read_b128 v[132:135], v146
	ds_read_b128 v[136:139], v146 offset:4096
	ds_read_b128 v[140:143], v146 offset:8192
	v_add_u32_e32 v150, v151, v158
	ds_read_b128 v[146:149], v146 offset:12288
	s_cmp_lt_u32 s48, 15
	s_mov_b64 s[18:19], -1
	s_cbranch_scc1 .LBB0_472
	s_add_i32 s50, s49, 0x10000
	s_mov_b64 s[18:19], 0

.LBB0_725:
	v_add_u32_e32 v162, v166, v189
	v_add_u32_e32 v167, v144, v189
	s_waitcnt lgkmcnt(3)
	v_mfma_f32_32x32x16_bf16 v[0:15], v[128:131], v[132:135], v[0:15]
	ds_read_b128 v[154:157], v162
	s_add_u32 s4, s4, 0x80
	s_addc_u32 s5, s5, 0
	s_add_i32 s45, s45, 1
	s_cmpk_lg_i32 s4, 0x800
	s_mov_b32 s46, s50
	v_mfma_f32_32x32x16_bf16 v[16:31], v[150:153], v[132:135], v[16:31]
	ds_read_b128 v[132:135], v162 offset:4096
	s_waitcnt lgkmcnt(4)
	v_mfma_f32_32x32x16_bf16 v[32:47], v[128:131], v[136:139], v[32:47]
	ds_read_b128 v[158:161], v162 offset:8192
	v_mfma_f32_32x32x16_bf16 v[48:63], v[150:153], v[136:139], v[48:63]
	ds_read_b128 v[136:139], v162 offset:12288
	s_waitcnt lgkmcnt(5)
	v_mfma_f32_32x32x16_bf16 v[64:79], v[128:131], v[140:143], v[64:79]
	ds_read_b128 v[162:165], v167 offset:32768
	v_mfma_f32_32x32x16_bf16 v[80:95], v[150:153], v[140:143], v[80:95]
	ds_read_b128 v[140:143], v167 offset:36864
	v_add_u32_e32 v167, v166, v190
	s_waitcnt lgkmcnt(6)
	v_mfma_f32_32x32x16_bf16 v[96:111], v[128:131], v[146:149], v[96:111]
	v_mfma_f32_32x32x16_bf16 v[112:127], v[150:153], v[146:149], v[112:127]
	s_waitcnt lgkmcnt(1)
	v_mfma_f32_32x32x16_bf16 v[0:15], v[162:165], v[154:157], v[0:15]
	ds_read_b128 v[128:131], v167
	s_waitcnt lgkmcnt(1)
	v_mfma_f32_32x32x16_bf16 v[16:31], v[140:143], v[154:157], v[16:31]
	ds_read_b128 v[146:149], v167 offset:4096
	v_mfma_f32_32x32x16_bf16 v[32:47], v[162:165], v[132:135], v[32:47]
	ds_read_b128 v[150:153], v167 offset:8192
	v_mfma_f32_32x32x16_bf16 v[48:63], v[140:143], v[132:135], v[48:63]
	ds_read_b128 v[132:135], v167 offset:12288
	v_add_u32_e32 v167, v144, v190
	v_add_u32_e32 v144, v144, v191
	v_mfma_f32_32x32x16_bf16 v[64:79], v[162:165], v[158:161], v[64:79]
	ds_read_b128 v[154:157], v167 offset:32768
	v_mfma_f32_32x32x16_bf16 v[80:95], v[140:143], v[158:161], v[80:95]
	ds_read_b128 v[158:161], v167 offset:36864
	v_mfma_f32_32x32x16_bf16 v[96:111], v[162:165], v[136:139], v[96:111]
	v_add_u32_e32 v162, v166, v191
	v_mfma_f32_32x32x16_bf16 v[112:127], v[140:143], v[136:139], v[112:127]
	s_waitcnt lgkmcnt(1)
	v_mfma_f32_32x32x16_bf16 v[0:15], v[154:157], v[128:131], v[0:15]
	ds_read_b128 v[136:139], v162
	s_waitcnt lgkmcnt(1)
	v_mfma_f32_32x32x16_bf16 v[16:31], v[158:161], v[128:131], v[16:31]
	ds_read_b128 v[128:131], v162 offset:4096
	v_mfma_f32_32x32x16_bf16 v[32:47], v[154:157], v[146:149], v[32:47]
	ds_read_b128 v[140:143], v162 offset:8192
	v_mfma_f32_32x32x16_bf16 v[48:63], v[158:161], v[146:149], v[48:63]
	ds_read_b128 v[146:149], v162 offset:12288
	v_mfma_f32_32x32x16_bf16 v[64:79], v[154:157], v[150:153], v[64:79]
	ds_read_b128 v[162:165], v144 offset:32768
	v_mfma_f32_32x32x16_bf16 v[80:95], v[158:161], v[150:153], v[80:95]
	ds_read_b128 v[150:153], v144 offset:36864
	v_mfma_f32_32x32x16_bf16 v[96:111], v[154:157], v[132:135], v[96:111]
	v_mfma_f32_32x32x16_bf16 v[112:127], v[158:161], v[132:135], v[112:127]
	s_waitcnt lgkmcnt(1)
	v_mfma_f32_32x32x16_bf16 v[0:15], v[162:165], v[136:139], v[0:15]
	s_waitcnt lgkmcnt(0)
	v_mfma_f32_32x32x16_bf16 v[16:31], v[150:153], v[136:139], v[16:31]
	v_mfma_f32_32x32x16_bf16 v[32:47], v[162:165], v[128:131], v[32:47]
	v_mfma_f32_32x32x16_bf16 v[48:63], v[150:153], v[128:131], v[48:63]
	v_mfma_f32_32x32x16_bf16 v[64:79], v[162:165], v[140:143], v[64:79]
	v_mfma_f32_32x32x16_bf16 v[80:95], v[150:153], v[140:143], v[80:95]
	v_mfma_f32_32x32x16_bf16 v[96:111], v[162:165], v[146:149], v[96:111]
	v_mfma_f32_32x32x16_bf16 v[112:127], v[150:153], v[146:149], v[112:127]
	s_cbranch_scc0 .LBB0_730

.Lkin_L1:
	s_and_b32 s6, s46, 0x10000
	v_or_b32_e32 v144, s6, v187
	v_add_u32_e32 v150, v144, v188
	ds_read_b128 v[128:131], v150 offset:32768
	ds_read_b128 v[150:153], v150 offset:36864
	v_add_u32_e32 v166, s6, v186
	v_add_u32_e32 v146, v166, v188
	ds_read_b128 v[132:135], v146
	ds_read_b128 v[136:139], v146 offset:4096
	ds_read_b128 v[140:143], v146 offset:8192
	ds_read_b128 v[146:149], v146 offset:12288
	s_cmp_lt_u32 s45, 15
	s_mov_b64 s[6:7], -1
	s_cbranch_scc1 .LBB0_728
	s_add_i32 s50, s46, 0x10000
	s_mov_b64 s[6:7], 0

.LBB0_897:
	s_waitcnt lgkmcnt(3)
	v_mfma_f32_32x32x16_bf16 v[48:63], v[130:133], v[134:137], v[48:63]
	ds_read_b128 v[166:169], v157
	s_add_u32 s16, s16, 0x80
	s_addc_u32 s17, s17, 0
	s_add_i32 s56, s56, 1
	s_cmpk_lg_i32 s16, 0x400
	s_mov_b32 s57, s58
	v_mfma_f32_32x32x16_bf16 v[32:47], v[162:165], v[134:137], v[32:47]
	ds_read_b128 v[134:137], v157 offset:4096
	s_waitcnt lgkmcnt(4)
	v_mfma_f32_32x32x16_bf16 v[16:31], v[130:133], v[138:141], v[16:31]
	ds_read_b128 v[170:173], v157 offset:8192
	v_mfma_f32_32x32x16_bf16 v[0:15], v[162:165], v[138:141], v[0:15]
	ds_read_b128 v[138:141], v157 offset:12288
	v_add_u32_e32 v157, v128, v154
	s_waitcnt lgkmcnt(5)
	v_mfma_f32_32x32x16_bf16 v[64:79], v[130:133], v[142:145], v[64:79]
	ds_read_b128 v[174:177], v157 offset:32768
	v_mfma_f32_32x32x16_bf16 v[80:95], v[162:165], v[142:145], v[80:95]
	ds_read_b128 v[142:145], v157 offset:36864
	v_add_u32_e32 v157, v180, v155
	s_waitcnt lgkmcnt(6)
	v_mfma_f32_32x32x16_bf16 v[96:111], v[130:133], v[158:161], v[96:111]
	v_mfma_f32_32x32x16_bf16 v[112:127], v[162:165], v[158:161], v[112:127]
	s_waitcnt lgkmcnt(1)
	v_mfma_f32_32x32x16_bf16 v[48:63], v[174:177], v[166:169], v[48:63]
	ds_read_b128 v[130:133], v157
	s_waitcnt lgkmcnt(1)
	v_mfma_f32_32x32x16_bf16 v[32:47], v[142:145], v[166:169], v[32:47]
	ds_read_b128 v[158:161], v157 offset:4096
	v_mfma_f32_32x32x16_bf16 v[16:31], v[174:177], v[134:137], v[16:31]
	ds_read_b128 v[162:165], v157 offset:8192
	v_mfma_f32_32x32x16_bf16 v[0:15], v[142:145], v[134:137], v[0:15]
	ds_read_b128 v[134:137], v157 offset:12288
	v_add_u32_e32 v157, v128, v155
	v_add_u32_e32 v128, v128, v156
	v_mfma_f32_32x32x16_bf16 v[64:79], v[174:177], v[170:173], v[64:79]
	ds_read_b128 v[166:169], v157 offset:32768
	v_mfma_f32_32x32x16_bf16 v[80:95], v[142:145], v[170:173], v[80:95]
	ds_read_b128 v[170:173], v157 offset:36864
	v_add_u32_e32 v157, v180, v156
	v_mfma_f32_32x32x16_bf16 v[96:111], v[174:177], v[138:141], v[96:111]
	v_mfma_f32_32x32x16_bf16 v[112:127], v[142:145], v[138:141], v[112:127]
	s_waitcnt lgkmcnt(1)
	v_mfma_f32_32x32x16_bf16 v[48:63], v[166:169], v[130:133], v[48:63]
	ds_read_b128 v[138:141], v157
	s_waitcnt lgkmcnt(1)
	v_mfma_f32_32x32x16_bf16 v[32:47], v[170:173], v[130:133], v[32:47]
	ds_read_b128 v[130:133], v157 offset:4096
	v_mfma_f32_32x32x16_bf16 v[16:31], v[166:169], v[158:161], v[16:31]
	ds_read_b128 v[142:145], v157 offset:8192
	v_mfma_f32_32x32x16_bf16 v[0:15], v[170:173], v[158:161], v[0:15]
	ds_read_b128 v[158:161], v157 offset:12288
	v_mfma_f32_32x32x16_bf16 v[64:79], v[166:169], v[162:165], v[64:79]
	ds_read_b128 v[174:177], v128 offset:32768
	v_mfma_f32_32x32x16_bf16 v[80:95], v[170:173], v[162:165], v[80:95]
	ds_read_b128 v[162:165], v128 offset:36864
	v_mfma_f32_32x32x16_bf16 v[96:111], v[166:169], v[134:137], v[96:111]
	v_mfma_f32_32x32x16_bf16 v[112:127], v[170:173], v[134:137], v[112:127]
	s_waitcnt lgkmcnt(1)
	v_mfma_f32_32x32x16_bf16 v[48:63], v[174:177], v[138:141], v[48:63]
	s_waitcnt lgkmcnt(0)
	v_mfma_f32_32x32x16_bf16 v[32:47], v[162:165], v[138:141], v[32:47]
	v_mfma_f32_32x32x16_bf16 v[16:31], v[174:177], v[130:133], v[16:31]
	v_mfma_f32_32x32x16_bf16 v[0:15], v[162:165], v[130:133], v[0:15]
	v_mfma_f32_32x32x16_bf16 v[64:79], v[174:177], v[142:145], v[64:79]
	v_mfma_f32_32x32x16_bf16 v[80:95], v[162:165], v[142:145], v[80:95]
	v_mfma_f32_32x32x16_bf16 v[96:111], v[174:177], v[158:161], v[96:111]
	v_mfma_f32_32x32x16_bf16 v[112:127], v[162:165], v[158:161], v[112:127]
	s_cbranch_scc0 .LBB0_902
.LBB0_898:
	s_waitcnt vmcnt(0)
	s_barrier
	s_and_b32 s20, s57, 0x10000
	v_or_b32_e32 v128, s20, v152
	v_add_u32_e32 v157, v128, v153
	ds_read_b128 v[130:133], v157 offset:32768
	ds_read_b128 v[162:165], v157 offset:36864
	v_add_u32_e32 v180, s20, v151
	v_add_u32_e32 v158, v180, v153
	ds_read_b128 v[134:137], v158
	ds_read_b128 v[138:141], v158 offset:4096
	ds_read_b128 v[142:145], v158 offset:8192
	v_add_u32_e32 v157, v180, v154
	ds_read_b128 v[158:161], v158 offset:12288
	s_cmp_lt_u32 s56, 7
	s_mov_b64 s[20:21], -1
	s_cbranch_scc1 .LBB0_900
	s_add_i32 s58, s57, 0x10000
	s_mov_b64 s[20:21], 0

.LBB0_911:
	s_waitcnt lgkmcnt(3)
	v_mfma_f32_32x32x16_bf16 v[48:63], v[130:133], v[134:137], v[48:63]
	ds_read_b128 v[166:169], v157
	s_add_u32 s18, s18, 0x80
	s_addc_u32 s19, s19, 0
	s_add_i32 s56, s56, 1
	s_cmpk_lg_i32 s18, 0x400
	s_mov_b32 s57, s58
	v_mfma_f32_32x32x16_bf16 v[32:47], v[162:165], v[134:137], v[32:47]
	ds_read_b128 v[134:137], v157 offset:4096
	s_waitcnt lgkmcnt(4)
	v_mfma_f32_32x32x16_bf16 v[16:31], v[130:133], v[138:141], v[16:31]
	ds_read_b128 v[170:173], v157 offset:8192
	v_mfma_f32_32x32x16_bf16 v[0:15], v[162:165], v[138:141], v[0:15]
	ds_read_b128 v[138:141], v157 offset:12288
	v_add_u32_e32 v157, v128, v154
	s_waitcnt lgkmcnt(5)
	v_mfma_f32_32x32x16_bf16 v[64:79], v[130:133], v[142:145], v[64:79]
	ds_read_b128 v[174:177], v157 offset:32768
	v_mfma_f32_32x32x16_bf16 v[80:95], v[162:165], v[142:145], v[80:95]
	ds_read_b128 v[142:145], v157 offset:36864
	v_add_u32_e32 v157, v180, v155
	s_waitcnt lgkmcnt(6)
	v_mfma_f32_32x32x16_bf16 v[96:111], v[130:133], v[158:161], v[96:111]
	v_mfma_f32_32x32x16_bf16 v[112:127], v[162:165], v[158:161], v[112:127]
	s_waitcnt lgkmcnt(1)
	v_mfma_f32_32x32x16_bf16 v[48:63], v[174:177], v[166:169], v[48:63]
	ds_read_b128 v[130:133], v157
	s_waitcnt lgkmcnt(1)
	v_mfma_f32_32x32x16_bf16 v[32:47], v[142:145], v[166:169], v[32:47]
	ds_read_b128 v[158:161], v157 offset:4096
	v_mfma_f32_32x32x16_bf16 v[16:31], v[174:177], v[134:137], v[16:31]
	ds_read_b128 v[162:165], v157 offset:8192
	v_mfma_f32_32x32x16_bf16 v[0:15], v[142:145], v[134:137], v[0:15]
	ds_read_b128 v[134:137], v157 offset:12288
	v_add_u32_e32 v157, v128, v155
	v_add_u32_e32 v128, v128, v156
	v_mfma_f32_32x32x16_bf16 v[64:79], v[174:177], v[170:173], v[64:79]
	ds_read_b128 v[166:169], v157 offset:32768
	v_mfma_f32_32x32x16_bf16 v[80:95], v[142:145], v[170:173], v[80:95]
	ds_read_b128 v[170:173], v157 offset:36864
	v_add_u32_e32 v157, v180, v156
	v_mfma_f32_32x32x16_bf16 v[96:111], v[174:177], v[138:141], v[96:111]
	v_mfma_f32_32x32x16_bf16 v[112:127], v[142:145], v[138:141], v[112:127]
	s_waitcnt lgkmcnt(1)
	v_mfma_f32_32x32x16_bf16 v[48:63], v[166:169], v[130:133], v[48:63]
	ds_read_b128 v[138:141], v157
	s_waitcnt lgkmcnt(1)
	v_mfma_f32_32x32x16_bf16 v[32:47], v[170:173], v[130:133], v[32:47]
	ds_read_b128 v[130:133], v157 offset:4096
	v_mfma_f32_32x32x16_bf16 v[16:31], v[166:169], v[158:161], v[16:31]
	ds_read_b128 v[142:145], v157 offset:8192
	v_mfma_f32_32x32x16_bf16 v[0:15], v[170:173], v[158:161], v[0:15]
	ds_read_b128 v[158:161], v157 offset:12288
	v_mfma_f32_32x32x16_bf16 v[64:79], v[166:169], v[162:165], v[64:79]
	ds_read_b128 v[174:177], v128 offset:32768
	v_mfma_f32_32x32x16_bf16 v[80:95], v[170:173], v[162:165], v[80:95]
	ds_read_b128 v[162:165], v128 offset:36864
	v_mfma_f32_32x32x16_bf16 v[96:111], v[166:169], v[134:137], v[96:111]
	v_mfma_f32_32x32x16_bf16 v[112:127], v[170:173], v[134:137], v[112:127]
	s_waitcnt lgkmcnt(1)
	v_mfma_f32_32x32x16_bf16 v[48:63], v[174:177], v[138:141], v[48:63]
	s_waitcnt lgkmcnt(0)
	v_mfma_f32_32x32x16_bf16 v[32:47], v[162:165], v[138:141], v[32:47]
	v_mfma_f32_32x32x16_bf16 v[16:31], v[174:177], v[130:133], v[16:31]
	v_mfma_f32_32x32x16_bf16 v[0:15], v[162:165], v[130:133], v[0:15]
	v_mfma_f32_32x32x16_bf16 v[64:79], v[174:177], v[142:145], v[64:79]
	v_mfma_f32_32x32x16_bf16 v[80:95], v[162:165], v[142:145], v[80:95]
	v_mfma_f32_32x32x16_bf16 v[96:111], v[174:177], v[158:161], v[96:111]
	v_mfma_f32_32x32x16_bf16 v[112:127], v[162:165], v[158:161], v[112:127]
	s_cbranch_scc0 .LBB0_916

.LBB0_981:
	s_waitcnt lgkmcnt(3)
	v_mfma_f32_32x32x16_bf16 v[48:63], v[130:133], v[134:137], v[48:63]
	ds_read_b128 v[166:169], v142
	s_add_u32 s0, s0, 0x80
	s_addc_u32 s1, s1, 0
	s_add_i32 s43, s43, 1
	s_cmpk_lg_i32 s0, 0x800
	s_mov_b32 s44, s45
	v_mfma_f32_32x32x16_bf16 v[32:47], v[162:165], v[134:137], v[32:47]
	ds_read_b128 v[134:137], v142 offset:4096
	s_waitcnt lgkmcnt(4)
	v_mfma_f32_32x32x16_bf16 v[16:31], v[130:133], v[138:141], v[16:31]
	ds_read_b128 v[170:173], v142 offset:8192
	v_mfma_f32_32x32x16_bf16 v[0:15], v[162:165], v[138:141], v[0:15]
	ds_read_b128 v[138:141], v142 offset:12288
	v_add_u32_e32 v142, v128, v150
	s_waitcnt lgkmcnt(5)
	v_mfma_f32_32x32x16_bf16 v[64:79], v[130:133], v[154:157], v[64:79]
	ds_read_b128 v[174:177], v142 offset:32768
	v_mfma_f32_32x32x16_bf16 v[80:95], v[162:165], v[154:157], v[80:95]
	ds_read_b128 v[154:157], v142 offset:36864
	v_add_u32_e32 v142, v143, v151
	s_waitcnt lgkmcnt(6)
	v_mfma_f32_32x32x16_bf16 v[96:111], v[130:133], v[158:161], v[96:111]
	v_mfma_f32_32x32x16_bf16 v[112:127], v[162:165], v[158:161], v[112:127]
	s_waitcnt lgkmcnt(1)
	v_mfma_f32_32x32x16_bf16 v[48:63], v[174:177], v[166:169], v[48:63]
	ds_read_b128 v[130:133], v142
	s_waitcnt lgkmcnt(1)
	v_mfma_f32_32x32x16_bf16 v[32:47], v[154:157], v[166:169], v[32:47]
	ds_read_b128 v[158:161], v142 offset:4096
	v_mfma_f32_32x32x16_bf16 v[16:31], v[174:177], v[134:137], v[16:31]
	ds_read_b128 v[162:165], v142 offset:8192
	v_mfma_f32_32x32x16_bf16 v[0:15], v[154:157], v[134:137], v[0:15]
	ds_read_b128 v[134:137], v142 offset:12288
	v_add_u32_e32 v142, v128, v151
	v_add_u32_e32 v128, v128, v152
	v_mfma_f32_32x32x16_bf16 v[64:79], v[174:177], v[170:173], v[64:79]
	ds_read_b128 v[166:169], v142 offset:32768
	v_mfma_f32_32x32x16_bf16 v[80:95], v[154:157], v[170:173], v[80:95]
	ds_read_b128 v[170:173], v142 offset:36864
	v_add_u32_e32 v142, v143, v152
	v_mfma_f32_32x32x16_bf16 v[96:111], v[174:177], v[138:141], v[96:111]
	v_mfma_f32_32x32x16_bf16 v[112:127], v[154:157], v[138:141], v[112:127]
	s_waitcnt lgkmcnt(1)
	v_mfma_f32_32x32x16_bf16 v[48:63], v[166:169], v[130:133], v[48:63]
	ds_read_b128 v[138:141], v142
	s_waitcnt lgkmcnt(1)
	v_mfma_f32_32x32x16_bf16 v[32:47], v[170:173], v[130:133], v[32:47]
	ds_read_b128 v[130:133], v142 offset:4096
	v_mfma_f32_32x32x16_bf16 v[16:31], v[166:169], v[158:161], v[16:31]
	ds_read_b128 v[154:157], v142 offset:8192
	v_mfma_f32_32x32x16_bf16 v[0:15], v[170:173], v[158:161], v[0:15]
	ds_read_b128 v[158:161], v142 offset:12288
	v_mfma_f32_32x32x16_bf16 v[64:79], v[166:169], v[162:165], v[64:79]
	ds_read_b128 v[174:177], v128 offset:32768
	v_mfma_f32_32x32x16_bf16 v[80:95], v[170:173], v[162:165], v[80:95]
	ds_read_b128 v[162:165], v128 offset:36864
	v_mfma_f32_32x32x16_bf16 v[96:111], v[166:169], v[134:137], v[96:111]
	v_mfma_f32_32x32x16_bf16 v[112:127], v[170:173], v[134:137], v[112:127]
	s_waitcnt lgkmcnt(1)
	v_mfma_f32_32x32x16_bf16 v[48:63], v[174:177], v[138:141], v[48:63]
	s_waitcnt lgkmcnt(0)
	v_mfma_f32_32x32x16_bf16 v[32:47], v[162:165], v[138:141], v[32:47]
	v_mfma_f32_32x32x16_bf16 v[16:31], v[174:177], v[130:133], v[16:31]
	v_mfma_f32_32x32x16_bf16 v[0:15], v[162:165], v[130:133], v[0:15]
	v_mfma_f32_32x32x16_bf16 v[64:79], v[174:177], v[154:157], v[64:79]
	v_mfma_f32_32x32x16_bf16 v[80:95], v[162:165], v[154:157], v[80:95]
	v_mfma_f32_32x32x16_bf16 v[96:111], v[174:177], v[158:161], v[96:111]
	v_mfma_f32_32x32x16_bf16 v[112:127], v[162:165], v[158:161], v[112:127]
	s_cbranch_scc0 .LBB0_986
.LBB0_982:
	s_waitcnt vmcnt(0)
	s_barrier
	s_and_b32 s10, s44, 0x10000
	v_or_b32_e32 v128, s10, v148
	v_add_u32_e32 v142, v128, v149
	ds_read_b128 v[130:133], v142 offset:32768
	ds_read_b128 v[162:165], v142 offset:36864
	v_add_u32_e32 v143, s10, v147
	v_add_u32_e32 v153, v143, v149
	ds_read_b128 v[134:137], v153
	ds_read_b128 v[138:141], v153 offset:4096
	ds_read_b128 v[154:157], v153 offset:8192
	v_add_u32_e32 v142, v143, v150
	ds_read_b128 v[158:161], v153 offset:12288
	s_cmp_lt_u32 s43, 15
	s_mov_b64 s[10:11], -1
	s_cbranch_scc1 .LBB0_984
	s_add_i32 s45, s44, 0x10000
	s_mov_b64 s[10:11], 0

.LBB0_1054:
	s_waitcnt lgkmcnt(3)
	v_mfma_f32_32x32x16_bf16 v[112:127], v[128:131], v[132:135], v[112:127]
	ds_read_b128 v[168:171], v150
	s_add_u32 s0, s0, 0x80
	s_addc_u32 s1, s1, 0
	s_add_i32 s47, s47, 1
	s_cmpk_lg_i32 s0, 0x800
	s_mov_b32 s48, s49
	v_mfma_f32_32x32x16_bf16 v[96:111], v[164:167], v[132:135], v[96:111]
	ds_read_b128 v[132:135], v150 offset:4096
	s_waitcnt lgkmcnt(4)
	v_mfma_f32_32x32x16_bf16 v[80:95], v[128:131], v[136:139], v[80:95]
	ds_read_b128 v[172:175], v150 offset:8192
	v_mfma_f32_32x32x16_bf16 v[64:79], v[164:167], v[136:139], v[64:79]
	ds_read_b128 v[136:139], v150 offset:12288
	v_add_u32_e32 v150, v144, v158
	s_waitcnt lgkmcnt(5)
	v_mfma_f32_32x32x16_bf16 v[48:63], v[128:131], v[140:143], v[48:63]
	ds_read_b128 v[180:183], v150 offset:32768
	v_mfma_f32_32x32x16_bf16 v[32:47], v[164:167], v[140:143], v[32:47]
	ds_read_b128 v[140:143], v150 offset:36864
	v_add_u32_e32 v150, v151, v159
	s_waitcnt lgkmcnt(6)
	v_mfma_f32_32x32x16_bf16 v[16:31], v[128:131], v[146:149], v[16:31]
	v_mfma_f32_32x32x16_bf16 v[0:15], v[164:167], v[146:149], v[0:15]
	s_waitcnt lgkmcnt(1)
	v_mfma_f32_32x32x16_bf16 v[112:127], v[180:183], v[168:171], v[112:127]
	ds_read_b128 v[128:131], v150
	s_waitcnt lgkmcnt(1)
	v_mfma_f32_32x32x16_bf16 v[96:111], v[140:143], v[168:171], v[96:111]
	ds_read_b128 v[146:149], v150 offset:4096
	v_mfma_f32_32x32x16_bf16 v[80:95], v[180:183], v[132:135], v[80:95]
	ds_read_b128 v[164:167], v150 offset:8192
	v_mfma_f32_32x32x16_bf16 v[64:79], v[140:143], v[132:135], v[64:79]
	ds_read_b128 v[132:135], v150 offset:12288
	v_add_u32_e32 v150, v144, v159
	v_add_u32_e32 v144, v144, v160
	v_mfma_f32_32x32x16_bf16 v[48:63], v[180:183], v[172:175], v[48:63]
	ds_read_b128 v[168:171], v150 offset:32768
	v_mfma_f32_32x32x16_bf16 v[32:47], v[140:143], v[172:175], v[32:47]
	ds_read_b128 v[172:175], v150 offset:36864
	v_add_u32_e32 v150, v151, v160
	v_mfma_f32_32x32x16_bf16 v[16:31], v[180:183], v[136:139], v[16:31]
	v_mfma_f32_32x32x16_bf16 v[0:15], v[140:143], v[136:139], v[0:15]
	s_waitcnt lgkmcnt(1)
	v_mfma_f32_32x32x16_bf16 v[112:127], v[168:171], v[128:131], v[112:127]
	ds_read_b128 v[136:139], v150
	s_waitcnt lgkmcnt(1)
	v_mfma_f32_32x32x16_bf16 v[96:111], v[172:175], v[128:131], v[96:111]
	ds_read_b128 v[128:131], v150 offset:4096
	v_mfma_f32_32x32x16_bf16 v[80:95], v[168:171], v[146:149], v[80:95]
	ds_read_b128 v[140:143], v150 offset:8192
	v_mfma_f32_32x32x16_bf16 v[64:79], v[172:175], v[146:149], v[64:79]
	ds_read_b128 v[146:149], v150 offset:12288
	v_mfma_f32_32x32x16_bf16 v[48:63], v[168:171], v[164:167], v[48:63]
	ds_read_b128 v[180:183], v144 offset:32768
	v_mfma_f32_32x32x16_bf16 v[32:47], v[172:175], v[164:167], v[32:47]
	ds_read_b128 v[164:167], v144 offset:36864
	v_mfma_f32_32x32x16_bf16 v[16:31], v[168:171], v[132:135], v[16:31]
	v_mfma_f32_32x32x16_bf16 v[0:15], v[172:175], v[132:135], v[0:15]
	s_waitcnt lgkmcnt(1)
	v_mfma_f32_32x32x16_bf16 v[112:127], v[180:183], v[136:139], v[112:127]
	s_waitcnt lgkmcnt(0)
	v_mfma_f32_32x32x16_bf16 v[96:111], v[164:167], v[136:139], v[96:111]
	v_mfma_f32_32x32x16_bf16 v[80:95], v[180:183], v[128:131], v[80:95]
	v_mfma_f32_32x32x16_bf16 v[64:79], v[164:167], v[128:131], v[64:79]
	v_mfma_f32_32x32x16_bf16 v[48:63], v[180:183], v[140:143], v[48:63]
	v_mfma_f32_32x32x16_bf16 v[32:47], v[164:167], v[140:143], v[32:47]
	v_mfma_f32_32x32x16_bf16 v[16:31], v[180:183], v[146:149], v[16:31]
	v_mfma_f32_32x32x16_bf16 v[0:15], v[164:167], v[146:149], v[0:15]
	s_cbranch_scc0 .LBB0_1059
.LBB0_1055:
	s_waitcnt vmcnt(0)
	s_barrier
	s_and_b32 s18, s48, 0x10000
	v_or_b32_e32 v144, s18, v156
	v_add_u32_e32 v150, v144, v157
	ds_read_b128 v[128:131], v150 offset:32768
	ds_read_b128 v[164:167], v150 offset:36864
	v_add_u32_e32 v151, s18, v155
	v_add_u32_e32 v146, v151, v157
	ds_read_b128 v[132:135], v146
	ds_read_b128 v[136:139], v146 offset:4096
	ds_read_b128 v[140:143], v146 offset:8192
	v_add_u32_e32 v150, v151, v158
	ds_read_b128 v[146:149], v146 offset:12288
	s_cmp_lt_u32 s47, 15
	s_mov_b64 s[18:19], -1
	s_cbranch_scc1 .LBB0_1057
	s_add_i32 s49, s48, 0x10000
	s_mov_b64 s[18:19], 0
